# group-barrier polls at the plain seams keep two poll loads in flight half a round trip apart (dedicated registers, no drain wait on exit): waiting workgroups observe the last flag sooner
# baseline (speedup 1.0000x reference)
; __device__ __forceinline__ unsigned xb_ld(unsigned* p)              { return __hip_atomic_load(p, __ATOMIC_RELAXED, __HIP_MEMORY_SCOPE_AGENT); }
; __device__ __forceinline__ unsigned xb_add(unsigned* p, unsigned v) { return __hip_atomic_fetch_add(p, v, __ATOMIC_RELAXED, __HIP_MEMORY_SCOPE_AGENT); }
; #define XB_SPIN(cond, bar) do { unsigned _sp = 0; while (cond) { __builtin_amdgcn_s_sleep(1); \
;     if ((++_sp & 255u) == 0u) { if (xb_ld(&(bar)[XB_TMO])) break; if (_sp > XB_SPIN_CAP) { atomicAdd(&(bar)[XB_TMO], 1u); break; } } } } while (0)
; __device__ __forceinline__ void xcc_local_barrier(unsigned* bar2, unsigned x, unsigned nloc, unsigned* tmobar) {
;     asm volatile("s_waitcnt vmcnt(0)" ::: "memory");
;     __syncthreads();
;     if (threadIdx.x == 0) {
;         const unsigned old = xb_add(&bar2[XB_XSUB(x)], 1u);
;         const unsigned gen = old / nloc;
;         if (old + 1u == (gen + 1u) * nloc) (void)xb_add(&bar2[XB_XGEN(x)], 1u);
;         else XB_SPIN(xb_ld(&bar2[XB_XGEN(x)]) == gen, tmobar);
;         __builtin_amdgcn_fence(__ATOMIC_ACQUIRE, "agent");
;         asm volatile("s_waitcnt vmcnt(0)" ::: "memory");
;     }
;     __syncthreads();
; }
.LBB0_612:
	s_and_b64 vcc, exec, s[40:41]
	s_cbranch_vccz .LBB0_632
	v_readlane_b32 s6, v238, 25
	s_nop 1
	v_mov_b32_e32 v2, s6
	ds_read_b32 v2, v2
	s_waitcnt vmcnt(0)
	v_readlane_b32 s6, v242, 38
	v_readlane_b32 s7, v242, 39
	s_waitcnt vmcnt(0) lgkmcnt(0)
	s_barrier
	s_and_saveexec_b64 s[40:41], s[6:7]
	s_cbranch_execz .LBB0_631
	s_add_i32 s101, s101, 1
	v_readlane_b32 s6, v239, 63
	v_readlane_b32 s7, v241, 0
	v_readlane_b32 s98, v242, 4
	v_mov_b32_e32 v3, s101
	s_nop 3
	s_lshr_b32 s98, s98, 6
	s_lshl_b32 s98, s98, 2
	v_mov_b32_e32 v4, s98
	global_store_dword v4, v3, s[6:7] offset:128 sc1
	buffer_inv sc1
	s_mov_b32 s100, 0
	global_load_dwordx4 v[244:247], v66, s[6:7] offset:128 sc1
	s_sleep 12
	global_load_dwordx4 v[248:251], v66, s[6:7] offset:128 sc1
.Lgrp_poll_1:
	s_waitcnt vmcnt(1)
	v_min_u32_e32 v244, v244, v245
	v_min3_u32 v244, v244, v246, v247
	s_nop 0
	v_readfirstlane_b32 s98, v244
	s_nop 3
	s_cmp_ge_u32 s98, s101
	s_cbranch_scc1 .Lgrp_done_1
	global_load_dwordx4 v[244:247], v66, s[6:7] offset:128 sc1
	s_waitcnt vmcnt(1)
	v_min_u32_e32 v248, v248, v249
	v_min3_u32 v248, v248, v250, v251
	s_nop 0
	v_readfirstlane_b32 s98, v248
	s_nop 3
	s_cmp_ge_u32 s98, s101
	s_cbranch_scc1 .Lgrp_done_1
	global_load_dwordx4 v[248:251], v66, s[6:7] offset:128 sc1
	s_add_i32 s100, s100, 1
	s_cmp_lt_u32 s100, 0x8000
	s_cbranch_scc1 .Lgrp_poll_1
.Lgrp_done_1:
.LBB0_631:
	s_or_b64 exec, exec, s[40:41]
	s_barrier

; __device__ __forceinline__ unsigned xb_ld(unsigned* p)              { return __hip_atomic_load(p, __ATOMIC_RELAXED, __HIP_MEMORY_SCOPE_AGENT); }
; __device__ __forceinline__ unsigned xb_add(unsigned* p, unsigned v) { return __hip_atomic_fetch_add(p, v, __ATOMIC_RELAXED, __HIP_MEMORY_SCOPE_AGENT); }
; #define XB_SPIN(cond, bar) do { unsigned _sp = 0; while (cond) { __builtin_amdgcn_s_sleep(1); \
;     if ((++_sp & 255u) == 0u) { if (xb_ld(&(bar)[XB_TMO])) break; if (_sp > XB_SPIN_CAP) { atomicAdd(&(bar)[XB_TMO], 1u); break; } } } } while (0)
; __device__ __forceinline__ void xcc_local_barrier(unsigned* bar2, unsigned x, unsigned nloc, unsigned* tmobar) {
;     asm volatile("s_waitcnt vmcnt(0)" ::: "memory");
;     __syncthreads();
;     if (threadIdx.x == 0) {
;         const unsigned old = xb_add(&bar2[XB_XSUB(x)], 1u);
;         const unsigned gen = old / nloc;
;         if (old + 1u == (gen + 1u) * nloc) (void)xb_add(&bar2[XB_XGEN(x)], 1u);
;         else XB_SPIN(xb_ld(&bar2[XB_XGEN(x)]) == gen, tmobar);
;         __builtin_amdgcn_fence(__ATOMIC_ACQUIRE, "agent");
;         asm volatile("s_waitcnt vmcnt(0)" ::: "memory");
;     }
;     __syncthreads();
; }
.LBB0_721:
	s_and_b64 vcc, exec, s[44:45]
	s_cbranch_vccz .LBB0_741
	v_readlane_b32 s6, v238, 25
	s_nop 1
	v_mov_b32_e32 v2, s6
	ds_read_b32 v2, v2
	s_waitcnt vmcnt(0)
	v_readlane_b32 s6, v242, 38
	v_readlane_b32 s7, v242, 39
	s_waitcnt vmcnt(0) lgkmcnt(0)
	s_barrier
	s_and_saveexec_b64 s[44:45], s[6:7]
	s_cbranch_execz .LBB0_740
	s_add_i32 s101, s101, 1
	v_readlane_b32 s6, v239, 63
	v_readlane_b32 s7, v241, 0
	v_readlane_b32 s98, v242, 4
	v_mov_b32_e32 v3, s101
	s_nop 3
	s_lshr_b32 s98, s98, 6
	s_lshl_b32 s98, s98, 2
	v_mov_b32_e32 v4, s98
	global_store_dword v4, v3, s[6:7] offset:128 sc1
	buffer_inv sc1
	s_mov_b32 s100, 0
	global_load_dwordx4 v[244:247], v66, s[6:7] offset:128 sc1
	s_sleep 12
	global_load_dwordx4 v[248:251], v66, s[6:7] offset:128 sc1

; __device__ __forceinline__ unsigned xb_ld(unsigned* p)              { return __hip_atomic_load(p, __ATOMIC_RELAXED, __HIP_MEMORY_SCOPE_AGENT); }
; __device__ __forceinline__ unsigned xb_add(unsigned* p, unsigned v) { return __hip_atomic_fetch_add(p, v, __ATOMIC_RELAXED, __HIP_MEMORY_SCOPE_AGENT); }
; #define XB_SPIN(cond, bar) do { unsigned _sp = 0; while (cond) { __builtin_amdgcn_s_sleep(1); \
;     if ((++_sp & 255u) == 0u) { if (xb_ld(&(bar)[XB_TMO])) break; if (_sp > XB_SPIN_CAP) { atomicAdd(&(bar)[XB_TMO], 1u); break; } } } } while (0)
; __device__ __forceinline__ void xcc_local_barrier(unsigned* bar2, unsigned x, unsigned nloc, unsigned* tmobar) {
;     asm volatile("s_waitcnt vmcnt(0)" ::: "memory");
;     __syncthreads();
;     if (threadIdx.x == 0) {
;         const unsigned old = xb_add(&bar2[XB_XSUB(x)], 1u);
;         const unsigned gen = old / nloc;
;         if (old + 1u == (gen + 1u) * nloc) (void)xb_add(&bar2[XB_XGEN(x)], 1u);
;         else XB_SPIN(xb_ld(&bar2[XB_XGEN(x)]) == gen, tmobar);
;         __builtin_amdgcn_fence(__ATOMIC_ACQUIRE, "agent");
;         asm volatile("s_waitcnt vmcnt(0)" ::: "memory");
;     }
;     __syncthreads();
; }
.Lgrp_done_2:
.LBB0_740:
	s_or_b64 exec, exec, s[44:45]
	s_barrier

; __device__ __forceinline__ unsigned xb_ld(unsigned* p)              { return __hip_atomic_load(p, __ATOMIC_RELAXED, __HIP_MEMORY_SCOPE_AGENT); }
; __device__ __forceinline__ unsigned xb_add(unsigned* p, unsigned v) { return __hip_atomic_fetch_add(p, v, __ATOMIC_RELAXED, __HIP_MEMORY_SCOPE_AGENT); }
; #define XB_SPIN(cond, bar) do { unsigned _sp = 0; while (cond) { __builtin_amdgcn_s_sleep(1); \
;     if ((++_sp & 255u) == 0u) { if (xb_ld(&(bar)[XB_TMO])) break; if (_sp > XB_SPIN_CAP) { atomicAdd(&(bar)[XB_TMO], 1u); break; } } } } while (0)
; __device__ __forceinline__ void xcc_local_barrier(unsigned* bar2, unsigned x, unsigned nloc, unsigned* tmobar) {
;     asm volatile("s_waitcnt vmcnt(0)" ::: "memory");
;     __syncthreads();
;     if (threadIdx.x == 0) {
;         const unsigned old = xb_add(&bar2[XB_XSUB(x)], 1u);
;         const unsigned gen = old / nloc;
;         if (old + 1u == (gen + 1u) * nloc) (void)xb_add(&bar2[XB_XGEN(x)], 1u);
;         else XB_SPIN(xb_ld(&bar2[XB_XGEN(x)]) == gen, tmobar);
;         __builtin_amdgcn_fence(__ATOMIC_ACQUIRE, "agent");
;         asm volatile("s_waitcnt vmcnt(0)" ::: "memory");
;     }
;     __syncthreads();
; }
.LBB0_874:
	s_and_b64 vcc, exec, s[38:39]
	s_cbranch_vccz .LBB0_894
	v_readlane_b32 s6, v238, 25
	s_nop 1
	v_mov_b32_e32 v2, s6
	ds_read_b32 v2, v2
	s_waitcnt vmcnt(0)
	v_readlane_b32 s6, v242, 38
	v_readlane_b32 s7, v242, 39
	s_waitcnt vmcnt(0) lgkmcnt(0)
	s_barrier
	s_and_saveexec_b64 s[38:39], s[6:7]
	s_cbranch_execz .LBB0_893
	v_readlane_b32 s6, v240, 60
	v_readlane_b32 s7, v240, 61
	v_mov_b32_e32 v3, 1
	s_nop 4
	global_atomic_add v66, v3, s[6:7] offset:576
	s_add_i32 s101, s101, 1
	v_readlane_b32 s6, v239, 63
	v_readlane_b32 s7, v241, 0
	v_readlane_b32 s98, v242, 4
	v_mov_b32_e32 v3, s101
	s_nop 3
	s_lshr_b32 s98, s98, 6
	s_lshl_b32 s98, s98, 2
	v_mov_b32_e32 v4, s98
	global_store_dword v4, v3, s[6:7] offset:128 sc1
	buffer_inv sc1
	s_mov_b32 s100, 0
	global_load_dwordx4 v[244:247], v66, s[6:7] offset:128 sc1
	s_sleep 12
	global_load_dwordx4 v[248:251], v66, s[6:7] offset:128 sc1

; __device__ __forceinline__ unsigned xb_ld(unsigned* p)              { return __hip_atomic_load(p, __ATOMIC_RELAXED, __HIP_MEMORY_SCOPE_AGENT); }
; __device__ __forceinline__ unsigned xb_add(unsigned* p, unsigned v) { return __hip_atomic_fetch_add(p, v, __ATOMIC_RELAXED, __HIP_MEMORY_SCOPE_AGENT); }
; #define XB_SPIN(cond, bar) do { unsigned _sp = 0; while (cond) { __builtin_amdgcn_s_sleep(1); \
;     if ((++_sp & 255u) == 0u) { if (xb_ld(&(bar)[XB_TMO])) break; if (_sp > XB_SPIN_CAP) { atomicAdd(&(bar)[XB_TMO], 1u); break; } } } } while (0)
; __device__ __forceinline__ void xcc_local_barrier(unsigned* bar2, unsigned x, unsigned nloc, unsigned* tmobar) {
;     asm volatile("s_waitcnt vmcnt(0)" ::: "memory");
;     __syncthreads();
;     if (threadIdx.x == 0) {
;         const unsigned old = xb_add(&bar2[XB_XSUB(x)], 1u);
;         const unsigned gen = old / nloc;
;         if (old + 1u == (gen + 1u) * nloc) (void)xb_add(&bar2[XB_XGEN(x)], 1u);
;         else XB_SPIN(xb_ld(&bar2[XB_XGEN(x)]) == gen, tmobar);
;         __builtin_amdgcn_fence(__ATOMIC_ACQUIRE, "agent");
;         asm volatile("s_waitcnt vmcnt(0)" ::: "memory");
;     }
;     __syncthreads();
; }
.Lgrp_done_3:
.LBB0_893:
	s_or_b64 exec, exec, s[38:39]
	s_barrier

; __device__ __forceinline__ unsigned xb_ld(unsigned* p)              { return __hip_atomic_load(p, __ATOMIC_RELAXED, __HIP_MEMORY_SCOPE_AGENT); }
; __device__ __forceinline__ unsigned xb_add(unsigned* p, unsigned v) { return __hip_atomic_fetch_add(p, v, __ATOMIC_RELAXED, __HIP_MEMORY_SCOPE_AGENT); }
; #define XB_SPIN(cond, bar) do { unsigned _sp = 0; while (cond) { __builtin_amdgcn_s_sleep(1); \
;     if ((++_sp & 255u) == 0u) { if (xb_ld(&(bar)[XB_TMO])) break; if (_sp > XB_SPIN_CAP) { atomicAdd(&(bar)[XB_TMO], 1u); break; } } } } while (0)
; __device__ __forceinline__ void xcc_local_barrier(unsigned* bar2, unsigned x, unsigned nloc, unsigned* tmobar) {
;     asm volatile("s_waitcnt vmcnt(0)" ::: "memory");
;     __syncthreads();
;     if (threadIdx.x == 0) {
;         const unsigned old = xb_add(&bar2[XB_XSUB(x)], 1u);
;         const unsigned gen = old / nloc;
;         if (old + 1u == (gen + 1u) * nloc) (void)xb_add(&bar2[XB_XGEN(x)], 1u);
;         else XB_SPIN(xb_ld(&bar2[XB_XGEN(x)]) == gen, tmobar);
;         __builtin_amdgcn_fence(__ATOMIC_ACQUIRE, "agent");
;         asm volatile("s_waitcnt vmcnt(0)" ::: "memory");
;     }
;     __syncthreads();
; }
.LBB0_1044:
	s_and_b64 vcc, exec, s[36:37]
	s_cbranch_vccz .LBB0_1064
	v_readlane_b32 s6, v238, 25
	s_nop 1
	v_mov_b32_e32 v2, s6
	ds_read_b32 v2, v2
	s_waitcnt vmcnt(0)
	v_readlane_b32 s6, v242, 38
	v_readlane_b32 s7, v242, 39
	s_waitcnt vmcnt(0) lgkmcnt(0)
	s_barrier
	s_and_saveexec_b64 s[36:37], s[6:7]
	s_cbranch_execz .LBB0_1063
	s_add_i32 s101, s101, 1
	v_readlane_b32 s6, v239, 63
	v_readlane_b32 s7, v241, 0
	v_readlane_b32 s98, v242, 4
	v_mov_b32_e32 v3, s101
	s_nop 3
	s_lshr_b32 s98, s98, 6
	s_lshl_b32 s98, s98, 2
	v_mov_b32_e32 v4, s98
	global_store_dword v4, v3, s[6:7] offset:128 sc1
	buffer_inv sc1
	s_mov_b32 s100, 0
	global_load_dwordx4 v[244:247], v66, s[6:7] offset:128 sc1
	s_sleep 12
	global_load_dwordx4 v[248:251], v66, s[6:7] offset:128 sc1

; __device__ __forceinline__ unsigned xb_ld(unsigned* p)              { return __hip_atomic_load(p, __ATOMIC_RELAXED, __HIP_MEMORY_SCOPE_AGENT); }
; __device__ __forceinline__ unsigned xb_add(unsigned* p, unsigned v) { return __hip_atomic_fetch_add(p, v, __ATOMIC_RELAXED, __HIP_MEMORY_SCOPE_AGENT); }
; #define XB_SPIN(cond, bar) do { unsigned _sp = 0; while (cond) { __builtin_amdgcn_s_sleep(1); \
;     if ((++_sp & 255u) == 0u) { if (xb_ld(&(bar)[XB_TMO])) break; if (_sp > XB_SPIN_CAP) { atomicAdd(&(bar)[XB_TMO], 1u); break; } } } } while (0)
; __device__ __forceinline__ void xcc_local_barrier(unsigned* bar2, unsigned x, unsigned nloc, unsigned* tmobar) {
;     asm volatile("s_waitcnt vmcnt(0)" ::: "memory");
;     __syncthreads();
;     if (threadIdx.x == 0) {
;         const unsigned old = xb_add(&bar2[XB_XSUB(x)], 1u);
;         const unsigned gen = old / nloc;
;         if (old + 1u == (gen + 1u) * nloc) (void)xb_add(&bar2[XB_XGEN(x)], 1u);
;         else XB_SPIN(xb_ld(&bar2[XB_XGEN(x)]) == gen, tmobar);
;         __builtin_amdgcn_fence(__ATOMIC_ACQUIRE, "agent");
;         asm volatile("s_waitcnt vmcnt(0)" ::: "memory");
;     }
;     __syncthreads();
; }
.Lgrp_done_4:
.LBB0_1063:
	s_or_b64 exec, exec, s[36:37]
	s_barrier
